# seams: L1 invalidate issued at barrier entry
# speedup vs baseline: 1.0185x; 1.0136x over previous
; __device__ __forceinline__ unsigned xb_ld(unsigned* p)              { return __hip_atomic_load(p, __ATOMIC_RELAXED, __HIP_MEMORY_SCOPE_AGENT); }
; __device__ __forceinline__ void xcd_barrier_complete(unsigned* bar, unsigned x, unsigned& nloc, unsigned& nx) {
;     const unsigned G = gridDim.x * gridDim.y * gridDim.z;
;     unsigned sum, cnt, mine, sp = 0u;
;     for (;;) {
;         sum = 0u; cnt = 0u; mine = 0u;
; #pragma unroll
;         for (unsigned j = 0; j < 16; ++j) { const unsigned c = xb_ld(&bar[XB_XCNT(j)]); sum += c; cnt += (c > 0u) ? 1u : 0u; mine = (j == x) ? c : mine; }
; __device__ __forceinline__ void xcd_barrier(const XcdBarrier& b) {
;     asm volatile("s_waitcnt vmcnt(0)" ::: "memory");
;     __syncthreads();
;     if (threadIdx.x == 0) {
;         unsigned* bar = b.bar;
;         __builtin_amdgcn_s_waitcnt(0);
;         unsigned nloc = b.st[0], nx = b.st[1];
;         if (nloc == 0u) { xcd_barrier_complete(bar, b.x, nloc, nx); b.st[0] = nloc; b.st[1] = nx; }
.LBB0_144:
	s_cmp_lt_i32 s56, 2
	s_cselect_b64 s[10:11], -1, 0
	s_cmp_gt_i32 s57, 1
	s_cselect_b64 s[0:1], -1, 0
	s_and_b64 s[0:1], s[10:11], s[0:1]
	s_andn2_b64 vcc, exec, s[0:1]
	s_cbranch_vccnz .LBB0_443
	s_andn2_b64 vcc, exec, s[4:5]
	s_cbranch_vccnz .LBB0_199
	s_getreg_b32 s3, hwreg(HW_REG_XCC_ID, 0, 4)
	s_waitcnt vmcnt(0)
	v_cmp_eq_u32_e32 vcc, 0, v178
	s_waitcnt lgkmcnt(0)
	s_barrier
	s_and_saveexec_b64 s[0:1], vcc
	s_cbranch_execz .LBB0_198
	buffer_inv sc1
	s_add_i32 s4, 0, 0x23ff0
	v_mov_b32_e32 v0, s4
	s_waitcnt vmcnt(0) expcnt(0) lgkmcnt(0)
	ds_read_b32 v2, v0
	s_add_i32 s4, 0, 0x23ff4
	v_mov_b32_e32 v0, s4
	ds_read_b32 v0, v0
	s_and_b32 s3, s3, 15
	s_waitcnt lgkmcnt(1)
	v_cmp_ne_u32_e32 vcc, 0, v2
	s_cbranch_vccnz .LBB0_162
	v_readlane_b32 s4, v252, 0
	s_mul_i32 s33, s4, s58
	s_add_u32 s4, s54, 0x22a2200
	s_addc_u32 s5, s55, 0
	s_add_u32 s6, s54, 0x22a2400
	s_addc_u32 s7, s55, 0
	s_add_u32 s8, s54, 0x22a2500
	s_addc_u32 s9, s55, 0
	s_add_u32 s14, s54, 0x22a2600
	s_addc_u32 s15, s55, 0
	s_add_u32 s24, s54, 0x22a2700
	s_addc_u32 s25, s55, 0
	s_add_u32 s26, s54, 0x22a2800
	s_addc_u32 s27, s55, 0
	s_add_u32 s28, s54, 0x22a2900
	s_addc_u32 s29, s55, 0
	s_add_u32 s30, s54, 0x22a2a00
	s_addc_u32 s31, s55, 0
	s_add_u32 s34, s54, 0x22a2b00
	s_addc_u32 s35, s55, 0
	s_add_u32 s46, s54, 0x22a2c00
	s_addc_u32 s47, s55, 0
	s_add_u32 s60, s54, 0x22a2d00
	s_addc_u32 s61, s55, 0
	s_add_u32 s62, s54, 0x22a2e00
	s_addc_u32 s63, s55, 0
	s_add_u32 s64, s54, 0x22a2f00
	s_addc_u32 s65, s55, 0
	s_add_u32 s66, s54, 0x22a3000
	s_addc_u32 s67, s55, 0
	s_add_u32 s68, s54, 0x22a3100
	s_addc_u32 s69, s55, 0
	s_add_u32 s70, s54, 0x22a3200
	s_addc_u32 s71, s55, 0
	s_add_u32 s72, s54, 0x22a3300
	s_mul_i32 s33, s33, s59
	s_addc_u32 s73, s55, 0
	s_mov_b32 s80, 1
	v_mov_b32_e32 v16, 0
	s_branch .LBB0_150

; __device__ __forceinline__ unsigned xb_ld(unsigned* p)              { return __hip_atomic_load(p, __ATOMIC_RELAXED, __HIP_MEMORY_SCOPE_AGENT); }
; #define XB_SPIN(cond, bar) do { unsigned _sp = 0; while (cond) { __builtin_amdgcn_s_sleep(1); \
;     if ((++_sp & 255u) == 0u) { if (xb_ld(&(bar)[XB_TMO])) break; if (_sp > XB_SPIN_CAP) { atomicAdd(&(bar)[XB_TMO], 1u); break; } } } } while (0)
; __device__ __forceinline__ void xcd_barrier(const XcdBarrier& b) {
;     ...
;             XB_SPIN(xb_ld(&bar[XB_XGEN(b.x)]) == gen, bar);
;             __builtin_amdgcn_fence(__ATOMIC_ACQUIRE, "agent");
;             asm volatile("s_waitcnt vmcnt(0)" ::: "memory");
.LBB0_177:
	s_or_b64 exec, exec, s[8:9]
	s_waitcnt vmcnt(0)
	s_waitcnt vmcnt(0)

; __device__ __forceinline__ unsigned xb_ld(unsigned* p)              { return __hip_atomic_load(p, __ATOMIC_RELAXED, __HIP_MEMORY_SCOPE_AGENT); }
; __device__ __forceinline__ unsigned xb_add(unsigned* p, unsigned v) { return __hip_atomic_fetch_add(p, v, __ATOMIC_RELAXED, __HIP_MEMORY_SCOPE_AGENT); }
; #define XB_SPIN(cond, bar) do { unsigned _sp = 0; while (cond) { __builtin_amdgcn_s_sleep(1); \
;     if ((++_sp & 255u) == 0u) { if (xb_ld(&(bar)[XB_TMO])) break; if (_sp > XB_SPIN_CAP) { atomicAdd(&(bar)[XB_TMO], 1u); break; } } } } while (0)
; __device__ __forceinline__ void xcd_barrier(const XcdBarrier& b) {
;     ...
;             __builtin_amdgcn_fence(__ATOMIC_RELEASE, "agent");
;             asm volatile("s_waitcnt vmcnt(0)" ::: "memory");
;             const unsigned og = xb_add(&bar[XB_TOP], 1u);
;             const unsigned tg = og / nx;
;             if (og + 1u == (tg + 1u) * nx) xb_add(&bar[XB_TOPGEN], 1u);
;             else XB_SPIN(xb_ld(&bar[XB_TOPGEN]) == tg, bar);
;             __builtin_amdgcn_fence(__ATOMIC_ACQUIRE, "agent");
;             xb_add(&bar[XB_XGEN(b.x)], 1u);
;             asm volatile("s_waitcnt vmcnt(0)" ::: "memory");
.LBB0_195:
	s_or_b64 exec, exec, s[6:7]
	s_mov_b64 s[6:7], exec
	v_mbcnt_lo_u32_b32 v0, s6, 0
	v_mbcnt_hi_u32_b32 v0, s7, v0
	v_cmp_eq_u32_e32 vcc, 0, v0
	s_waitcnt vmcnt(0)
	s_and_saveexec_b64 s[8:9], vcc
	s_cbranch_execz .LBB0_197
	s_bcnt1_i32_b64 s3, s[6:7]
	v_mov_b32_e32 v0, 0x2000
	v_mov_b32_e32 v1, s3
	global_atomic_add v0, v1, s[4:5] offset:1024

; __device__ __forceinline__ unsigned xb_ld(unsigned* p)              { return __hip_atomic_load(p, __ATOMIC_RELAXED, __HIP_MEMORY_SCOPE_AGENT); }
; __device__ __forceinline__ void xcd_barrier_complete(unsigned* bar, unsigned x, unsigned& nloc, unsigned& nx) {
;     const unsigned G = gridDim.x * gridDim.y * gridDim.z;
;     unsigned sum, cnt, mine, sp = 0u;
;     for (;;) {
;         sum = 0u; cnt = 0u; mine = 0u;
; #pragma unroll
;         for (unsigned j = 0; j < 16; ++j) { const unsigned c = xb_ld(&bar[XB_XCNT(j)]); sum += c; cnt += (c > 0u) ? 1u : 0u; mine = (j == x) ? c : mine; }
; __device__ __forceinline__ void xcd_barrier(const XcdBarrier& b) {
;     asm volatile("s_waitcnt vmcnt(0)" ::: "memory");
;     __syncthreads();
;     if (threadIdx.x == 0) {
;         unsigned* bar = b.bar;
;         __builtin_amdgcn_s_waitcnt(0);
;         unsigned nloc = b.st[0], nx = b.st[1];
;         if (nloc == 0u) { xcd_barrier_complete(bar, b.x, nloc, nx); b.st[0] = nloc; b.st[1] = nx; }
.LBB0_443:
	s_cmp_lt_i32 s56, 3
	s_waitcnt lgkmcnt(0)
	s_cselect_b64 s[14:15], -1, 0
	s_cmp_gt_i32 s57, 2
	s_cselect_b64 s[0:1], -1, 0
	s_and_b64 s[0:1], s[14:15], s[0:1]
	s_andn2_b64 vcc, exec, s[0:1]
	s_cbranch_vccnz .LBB0_545
	s_and_b64 vcc, exec, s[10:11]
	s_cbranch_vccz .LBB0_498
	s_getreg_b32 s3, hwreg(HW_REG_XCC_ID, 0, 4)
	s_waitcnt vmcnt(0)
	v_cmp_eq_u32_e32 vcc, 0, v178
	s_waitcnt vmcnt(0)
	s_barrier
	s_and_saveexec_b64 s[0:1], vcc
	s_cbranch_execz .LBB0_497
	buffer_inv sc1
	s_add_i32 s4, 0, 0x23ff0
	v_mov_b32_e32 v0, s4
	s_waitcnt vmcnt(0) expcnt(0) lgkmcnt(0)
	ds_read_b32 v2, v0
	s_add_i32 s4, 0, 0x23ff4
	v_mov_b32_e32 v0, s4
	ds_read_b32 v0, v0
	s_and_b32 s3, s3, 15
	s_waitcnt lgkmcnt(1)
	v_cmp_ne_u32_e32 vcc, 0, v2
	s_cbranch_vccnz .LBB0_461
	v_readlane_b32 s4, v252, 0
	s_mul_i32 s33, s4, s58
	s_add_u32 s4, s54, 0x22a2200
	s_addc_u32 s5, s55, 0
	s_add_u32 s6, s54, 0x22a2400
	s_addc_u32 s7, s55, 0
	s_add_u32 s8, s54, 0x22a2500
	s_addc_u32 s9, s55, 0
	s_add_u32 s10, s54, 0x22a2600
	s_addc_u32 s11, s55, 0
	s_add_u32 s24, s54, 0x22a2700
	s_addc_u32 s25, s55, 0
	s_add_u32 s26, s54, 0x22a2800
	s_addc_u32 s27, s55, 0
	s_add_u32 s28, s54, 0x22a2900
	s_addc_u32 s29, s55, 0
	s_add_u32 s30, s54, 0x22a2a00
	s_addc_u32 s31, s55, 0
	s_add_u32 s34, s54, 0x22a2b00
	s_addc_u32 s35, s55, 0
	s_add_u32 s46, s54, 0x22a2c00
	s_addc_u32 s47, s55, 0
	s_add_u32 s60, s54, 0x22a2d00
	s_addc_u32 s61, s55, 0
	s_add_u32 s62, s54, 0x22a2e00
	s_addc_u32 s63, s55, 0
	s_add_u32 s64, s54, 0x22a2f00
	s_addc_u32 s65, s55, 0
	s_add_u32 s66, s54, 0x22a3000
	s_addc_u32 s67, s55, 0
	s_add_u32 s68, s54, 0x22a3100
	s_addc_u32 s69, s55, 0
	s_add_u32 s70, s54, 0x22a3200
	s_addc_u32 s71, s55, 0
	s_add_u32 s72, s54, 0x22a3300
	s_mul_i32 s33, s33, s59
	s_addc_u32 s73, s55, 0
	s_mov_b32 s80, 1
	v_mov_b32_e32 v16, 0
	s_branch .LBB0_449

; __device__ __forceinline__ unsigned xb_ld(unsigned* p)              { return __hip_atomic_load(p, __ATOMIC_RELAXED, __HIP_MEMORY_SCOPE_AGENT); }
; __device__ __forceinline__ void xcd_barrier_complete(unsigned* bar, unsigned x, unsigned& nloc, unsigned& nx) {
;     const unsigned G = gridDim.x * gridDim.y * gridDim.z;
;     unsigned sum, cnt, mine, sp = 0u;
;     for (;;) {
;         sum = 0u; cnt = 0u; mine = 0u;
; #pragma unroll
;         for (unsigned j = 0; j < 16; ++j) { const unsigned c = xb_ld(&bar[XB_XCNT(j)]); sum += c; cnt += (c > 0u) ? 1u : 0u; mine = (j == x) ? c : mine; }
; __device__ __forceinline__ void xcd_barrier(const XcdBarrier& b) {
;     asm volatile("s_waitcnt vmcnt(0)" ::: "memory");
;     __syncthreads();
;     if (threadIdx.x == 0) {
;         unsigned* bar = b.bar;
;         __builtin_amdgcn_s_waitcnt(0);
;         unsigned nloc = b.st[0], nx = b.st[1];
;         if (nloc == 0u) { xcd_barrier_complete(bar, b.x, nloc, nx); b.st[0] = nloc; b.st[1] = nx; }
.LBB0_545:
	s_cmp_lt_i32 s56, 4
	s_cselect_b64 s[0:1], -1, 0
	s_cmp_gt_i32 s57, 3
	s_cselect_b64 s[4:5], -1, 0
	s_and_b64 s[4:5], s[0:1], s[4:5]
	s_andn2_b64 vcc, exec, s[4:5]
	s_cbranch_vccnz .LBB0_670
	s_andn2_b64 vcc, exec, s[14:15]
	s_cbranch_vccnz .LBB0_558
	s_getreg_b32 s3, hwreg(HW_REG_XCC_ID, 0, 4)
	s_waitcnt vmcnt(0)
	v_cmp_eq_u32_e32 vcc, 0, v178
	s_waitcnt vmcnt(0)
	s_barrier
	s_and_saveexec_b64 s[4:5], vcc
	s_cbranch_execz .LBB0_631
	buffer_inv sc1
	s_add_i32 s6, 0, 0x23ff0
	v_mov_b32_e32 v0, s6
	s_waitcnt vmcnt(0) expcnt(0) lgkmcnt(0)
	ds_read_b32 v2, v0
	s_add_i32 s6, 0, 0x23ff4
	v_mov_b32_e32 v0, s6
	ds_read_b32 v0, v0
	s_and_b32 s3, s3, 15
	s_waitcnt lgkmcnt(1)
	v_cmp_ne_u32_e32 vcc, 0, v2
	s_cbranch_vccnz .LBB0_595
	v_readlane_b32 s6, v252, 0
	s_mul_i32 s33, s6, s58
	s_add_u32 s6, s54, 0x22a2200
	s_addc_u32 s7, s55, 0
	s_add_u32 s8, s54, 0x22a2400
	s_addc_u32 s9, s55, 0
	s_add_u32 s10, s54, 0x22a2500
	s_addc_u32 s11, s55, 0
	s_add_u32 s14, s54, 0x22a2600
	s_addc_u32 s15, s55, 0
	s_add_u32 s24, s54, 0x22a2700
	s_addc_u32 s25, s55, 0
	s_add_u32 s26, s54, 0x22a2800
	s_addc_u32 s27, s55, 0
	s_add_u32 s28, s54, 0x22a2900
	s_addc_u32 s29, s55, 0
	s_add_u32 s30, s54, 0x22a2a00
	s_addc_u32 s31, s55, 0
	s_add_u32 s34, s54, 0x22a2b00
	s_addc_u32 s35, s55, 0
	s_add_u32 s40, s54, 0x22a2c00
	s_addc_u32 s41, s55, 0
	s_add_u32 s42, s54, 0x22a2d00
	s_addc_u32 s43, s55, 0
	s_add_u32 s44, s54, 0x22a2e00
	s_addc_u32 s45, s55, 0
	s_add_u32 s46, s54, 0x22a2f00
	s_addc_u32 s47, s55, 0
	s_add_u32 s60, s54, 0x22a3000
	s_addc_u32 s61, s55, 0
	s_add_u32 s62, s54, 0x22a3100
	s_addc_u32 s63, s55, 0
	s_add_u32 s64, s54, 0x22a3200
	s_addc_u32 s65, s55, 0
	s_add_u32 s66, s54, 0x22a3300
	s_mul_i32 s33, s33, s59
	s_addc_u32 s67, s55, 0
	s_mov_b32 s74, 1
	v_mov_b32_e32 v16, 0
	s_branch .LBB0_551

; __device__ __forceinline__ unsigned xb_ld(unsigned* p)              { return __hip_atomic_load(p, __ATOMIC_RELAXED, __HIP_MEMORY_SCOPE_AGENT); }
; #define XB_SPIN(cond, bar) do { unsigned _sp = 0; while (cond) { __builtin_amdgcn_s_sleep(1); \
;     if ((++_sp & 255u) == 0u) { if (xb_ld(&(bar)[XB_TMO])) break; if (_sp > XB_SPIN_CAP) { atomicAdd(&(bar)[XB_TMO], 1u); break; } } } } while (0)
; __device__ __forceinline__ void xcd_barrier(const XcdBarrier& b) {
;     ...
;             XB_SPIN(xb_ld(&bar[XB_XGEN(b.x)]) == gen, bar);
;             __builtin_amdgcn_fence(__ATOMIC_ACQUIRE, "agent");
;             asm volatile("s_waitcnt vmcnt(0)" ::: "memory");
.LBB0_610:
	s_or_b64 exec, exec, s[10:11]
	s_waitcnt vmcnt(0)
	s_waitcnt vmcnt(0)

; __device__ __forceinline__ unsigned xb_ld(unsigned* p)              { return __hip_atomic_load(p, __ATOMIC_RELAXED, __HIP_MEMORY_SCOPE_AGENT); }
; __device__ __forceinline__ unsigned xb_add(unsigned* p, unsigned v) { return __hip_atomic_fetch_add(p, v, __ATOMIC_RELAXED, __HIP_MEMORY_SCOPE_AGENT); }
; #define XB_SPIN(cond, bar) do { unsigned _sp = 0; while (cond) { __builtin_amdgcn_s_sleep(1); \
;     if ((++_sp & 255u) == 0u) { if (xb_ld(&(bar)[XB_TMO])) break; if (_sp > XB_SPIN_CAP) { atomicAdd(&(bar)[XB_TMO], 1u); break; } } } } while (0)
; __device__ __forceinline__ void xcd_barrier(const XcdBarrier& b) {
;     ...
;             __builtin_amdgcn_fence(__ATOMIC_RELEASE, "agent");
;             asm volatile("s_waitcnt vmcnt(0)" ::: "memory");
;             const unsigned og = xb_add(&bar[XB_TOP], 1u);
;             const unsigned tg = og / nx;
;             if (og + 1u == (tg + 1u) * nx) xb_add(&bar[XB_TOPGEN], 1u);
;             else XB_SPIN(xb_ld(&bar[XB_TOPGEN]) == tg, bar);
;             __builtin_amdgcn_fence(__ATOMIC_ACQUIRE, "agent");
;             xb_add(&bar[XB_XGEN(b.x)], 1u);
;             asm volatile("s_waitcnt vmcnt(0)" ::: "memory");
.LBB0_628:
	s_or_b64 exec, exec, s[8:9]
	s_mov_b64 s[8:9], exec
	v_mbcnt_lo_u32_b32 v0, s8, 0
	v_mbcnt_hi_u32_b32 v0, s9, v0
	v_cmp_eq_u32_e32 vcc, 0, v0
	s_waitcnt vmcnt(0)
	s_and_saveexec_b64 s[10:11], vcc
	s_cbranch_execz .LBB0_630
	s_bcnt1_i32_b64 s3, s[8:9]
	v_mov_b32_e32 v0, 0x2000
	v_mov_b32_e32 v1, s3
	global_atomic_add v0, v1, s[6:7] offset:1024

; __device__ __forceinline__ unsigned xb_ld(unsigned* p)              { return __hip_atomic_load(p, __ATOMIC_RELAXED, __HIP_MEMORY_SCOPE_AGENT); }
; __device__ __forceinline__ void xcd_barrier_complete(unsigned* bar, unsigned x, unsigned& nloc, unsigned& nx) {
;     const unsigned G = gridDim.x * gridDim.y * gridDim.z;
;     unsigned sum, cnt, mine, sp = 0u;
;     for (;;) {
;         sum = 0u; cnt = 0u; mine = 0u;
; #pragma unroll
;         for (unsigned j = 0; j < 16; ++j) { const unsigned c = xb_ld(&bar[XB_XCNT(j)]); sum += c; cnt += (c > 0u) ? 1u : 0u; mine = (j == x) ? c : mine; }
; __device__ __forceinline__ void xcd_barrier(const XcdBarrier& b) {
;     asm volatile("s_waitcnt vmcnt(0)" ::: "memory");
;     __syncthreads();
;     if (threadIdx.x == 0) {
;         unsigned* bar = b.bar;
;         __builtin_amdgcn_s_waitcnt(0);
;         unsigned nloc = b.st[0], nx = b.st[1];
;         if (nloc == 0u) { xcd_barrier_complete(bar, b.x, nloc, nx); b.st[0] = nloc; b.st[1] = nx; }
.LBB0_670:
	s_cmp_lt_i32 s56, 5
	s_cselect_b64 s[14:15], -1, 0
	s_cmp_gt_i32 s57, 4
	s_cselect_b64 s[4:5], -1, 0
	s_and_b64 s[4:5], s[14:15], s[4:5]
	s_andn2_b64 vcc, exec, s[4:5]
	s_cbranch_vccnz .LBB0_745
	s_andn2_b64 vcc, exec, s[0:1]
	s_cbranch_vccnz .LBB0_725
	s_getreg_b32 s3, hwreg(HW_REG_XCC_ID, 0, 4)
	s_waitcnt vmcnt(0)
	v_cmp_eq_u32_e32 vcc, 0, v178
	s_waitcnt vmcnt(0)
	s_barrier
	s_and_saveexec_b64 s[0:1], vcc
	s_cbranch_execz .LBB0_724
	buffer_inv sc1
	s_add_i32 s4, 0, 0x23ff0
	v_mov_b32_e32 v0, s4
	s_waitcnt vmcnt(0) expcnt(0) lgkmcnt(0)
	ds_read_b32 v2, v0
	s_add_i32 s4, 0, 0x23ff4
	v_mov_b32_e32 v0, s4
	ds_read_b32 v0, v0
	s_and_b32 s3, s3, 15
	s_waitcnt lgkmcnt(1)
	v_cmp_ne_u32_e32 vcc, 0, v2
	s_cbranch_vccnz .LBB0_688
	v_readlane_b32 s4, v252, 0
	s_mul_i32 s33, s4, s58
	s_add_u32 s4, s54, 0x22a2200
	s_addc_u32 s5, s55, 0
	s_add_u32 s6, s54, 0x22a2400
	s_addc_u32 s7, s55, 0
	s_add_u32 s8, s54, 0x22a2500
	s_addc_u32 s9, s55, 0
	s_add_u32 s10, s54, 0x22a2600
	s_addc_u32 s11, s55, 0
	s_add_u32 s20, s54, 0x22a2700
	s_addc_u32 s21, s55, 0
	s_add_u32 s24, s54, 0x22a2800
	s_addc_u32 s25, s55, 0
	s_add_u32 s26, s54, 0x22a2900
	s_addc_u32 s27, s55, 0
	s_add_u32 s28, s54, 0x22a2a00
	s_addc_u32 s29, s55, 0
	s_add_u32 s30, s54, 0x22a2b00
	s_addc_u32 s31, s55, 0
	s_add_u32 s34, s54, 0x22a2c00
	s_addc_u32 s35, s55, 0
	s_add_u32 s40, s54, 0x22a2d00
	s_addc_u32 s41, s55, 0
	s_add_u32 s42, s54, 0x22a2e00
	s_addc_u32 s43, s55, 0
	s_add_u32 s44, s54, 0x22a2f00
	s_addc_u32 s45, s55, 0
	s_add_u32 s46, s54, 0x22a3000
	s_addc_u32 s47, s55, 0
	s_add_u32 s60, s54, 0x22a3100
	s_addc_u32 s61, s55, 0
	s_add_u32 s62, s54, 0x22a3200
	s_addc_u32 s63, s55, 0
	s_add_u32 s64, s54, 0x22a3300
	s_mul_i32 s33, s33, s59
	s_addc_u32 s65, s55, 0
	s_mov_b32 s72, 1
	v_mov_b32_e32 v16, 0
	s_branch .LBB0_676

; __device__ __forceinline__ unsigned xb_ld(unsigned* p)              { return __hip_atomic_load(p, __ATOMIC_RELAXED, __HIP_MEMORY_SCOPE_AGENT); }
; __device__ __forceinline__ void xcd_barrier_complete(unsigned* bar, unsigned x, unsigned& nloc, unsigned& nx) {
;     const unsigned G = gridDim.x * gridDim.y * gridDim.z;
;     unsigned sum, cnt, mine, sp = 0u;
;     for (;;) {
;         sum = 0u; cnt = 0u; mine = 0u;
; #pragma unroll
;         for (unsigned j = 0; j < 16; ++j) { const unsigned c = xb_ld(&bar[XB_XCNT(j)]); sum += c; cnt += (c > 0u) ? 1u : 0u; mine = (j == x) ? c : mine; }
; __device__ __forceinline__ void xcd_barrier(const XcdBarrier& b) {
;     asm volatile("s_waitcnt vmcnt(0)" ::: "memory");
;     __syncthreads();
;     if (threadIdx.x == 0) {
;         unsigned* bar = b.bar;
;         __builtin_amdgcn_s_waitcnt(0);
;         unsigned nloc = b.st[0], nx = b.st[1];
;         if (nloc == 0u) { xcd_barrier_complete(bar, b.x, nloc, nx); b.st[0] = nloc; b.st[1] = nx; }
.LBB0_745:
	s_cmp_lt_i32 s56, 6
	s_cselect_b64 s[0:1], -1, 0
	s_cmp_gt_i32 s57, 5
	s_cselect_b64 s[4:5], -1, 0
	s_and_b64 s[0:1], s[0:1], s[4:5]
	s_andn2_b64 vcc, exec, s[0:1]
	s_cbranch_vccnz .LBB0_841
	s_andn2_b64 vcc, exec, s[14:15]
	s_cbranch_vccnz .LBB0_800
	s_getreg_b32 s3, hwreg(HW_REG_XCC_ID, 0, 4)
	s_waitcnt vmcnt(0)
	v_cmp_eq_u32_e32 vcc, 0, v178
	s_waitcnt vmcnt(0)
	s_barrier
	s_and_saveexec_b64 s[0:1], vcc
	s_cbranch_execz .LBB0_799
	buffer_inv sc1
	s_add_i32 s4, 0, 0x23ff0
	v_mov_b32_e32 v0, s4
	s_waitcnt vmcnt(0) expcnt(0) lgkmcnt(0)
	ds_read_b32 v2, v0
	s_add_i32 s4, 0, 0x23ff4
	v_mov_b32_e32 v0, s4
	ds_read_b32 v0, v0
	s_and_b32 s3, s3, 15
	s_waitcnt lgkmcnt(1)
	v_cmp_ne_u32_e32 vcc, 0, v2
	s_cbranch_vccnz .LBB0_763
	v_readlane_b32 s4, v252, 0
	s_mul_i32 s33, s4, s58
	s_add_u32 s4, s54, 0x22a2200
	s_addc_u32 s5, s55, 0
	s_add_u32 s6, s54, 0x22a2400
	s_addc_u32 s7, s55, 0
	s_add_u32 s8, s54, 0x22a2500
	s_addc_u32 s9, s55, 0
	s_add_u32 s10, s54, 0x22a2600
	s_addc_u32 s11, s55, 0
	s_add_u32 s14, s54, 0x22a2700
	s_addc_u32 s15, s55, 0
	s_add_u32 s16, s54, 0x22a2800
	s_addc_u32 s17, s55, 0
	s_add_u32 s18, s54, 0x22a2900
	s_addc_u32 s19, s55, 0
	s_add_u32 s20, s54, 0x22a2a00
	s_addc_u32 s21, s55, 0
	s_add_u32 s22, s54, 0x22a2b00
	s_addc_u32 s23, s55, 0
	s_add_u32 s24, s54, 0x22a2c00
	s_addc_u32 s25, s55, 0
	s_add_u32 s26, s54, 0x22a2d00
	s_addc_u32 s27, s55, 0
	s_add_u32 s28, s54, 0x22a2e00
	s_addc_u32 s29, s55, 0
	s_add_u32 s30, s54, 0x22a2f00
	s_addc_u32 s31, s55, 0
	s_add_u32 s34, s54, 0x22a3000
	s_addc_u32 s35, s55, 0
	s_add_u32 s40, s54, 0x22a3100
	s_addc_u32 s41, s55, 0
	s_add_u32 s42, s54, 0x22a3200
	s_addc_u32 s43, s55, 0
	s_add_u32 s44, s54, 0x22a3300
	s_mul_i32 s33, s33, s59
	s_addc_u32 s45, s55, 0
	s_mov_b32 s64, 1
	v_mov_b32_e32 v16, 0
	s_branch .LBB0_751

; __device__ __forceinline__ unsigned xb_ld(unsigned* p)              { return __hip_atomic_load(p, __ATOMIC_RELAXED, __HIP_MEMORY_SCOPE_AGENT); }
; __device__ __forceinline__ void xcd_barrier_complete(unsigned* bar, unsigned x, unsigned& nloc, unsigned& nx) {
;     const unsigned G = gridDim.x * gridDim.y * gridDim.z;
;     unsigned sum, cnt, mine, sp = 0u;
;     for (;;) {
;         sum = 0u; cnt = 0u; mine = 0u;
; #pragma unroll
;         for (unsigned j = 0; j < 16; ++j) { const unsigned c = xb_ld(&bar[XB_XCNT(j)]); sum += c; cnt += (c > 0u) ? 1u : 0u; mine = (j == x) ? c : mine; }
; __device__ __forceinline__ void xcd_barrier(const XcdBarrier& b) {
;     asm volatile("s_waitcnt vmcnt(0)" ::: "memory");
;     __syncthreads();
;     if (threadIdx.x == 0) {
;         unsigned* bar = b.bar;
;         __builtin_amdgcn_s_waitcnt(0);
;         unsigned nloc = b.st[0], nx = b.st[1];
;         if (nloc == 0u) { xcd_barrier_complete(bar, b.x, nloc, nx); b.st[0] = nloc; b.st[1] = nx; }
.LBB0_841:
	s_cmp_lt_i32 s56, 8
	s_cselect_b64 s[6:7], -1, 0
	s_cmp_gt_i32 s57, 7
	s_cselect_b64 s[0:1], -1, 0
	s_and_b64 s[0:1], s[6:7], s[0:1]
	s_andn2_b64 vcc, exec, s[0:1]
	s_cbranch_vccnz .LBB0_934
	s_cmp_gt_i32 s56, 6
	s_cbranch_scc1 .LBB0_896
	s_getreg_b32 s3, hwreg(HW_REG_XCC_ID, 0, 4)
	s_waitcnt vmcnt(0)
	v_cmp_eq_u32_e32 vcc, 0, v178
	s_waitcnt vmcnt(0)
	s_barrier
	s_and_saveexec_b64 s[0:1], vcc
	s_cbranch_execz .LBB0_895
	buffer_inv sc1
	s_add_i32 s4, 0, 0x23ff0
	v_mov_b32_e32 v0, s4
	s_waitcnt vmcnt(0) expcnt(0) lgkmcnt(0)
	ds_read_b32 v2, v0
	s_add_i32 s4, 0, 0x23ff4
	v_mov_b32_e32 v0, s4
	ds_read_b32 v0, v0
	s_and_b32 s3, s3, 15
	s_waitcnt lgkmcnt(1)
	v_cmp_ne_u32_e32 vcc, 0, v2
	s_cbranch_vccnz .LBB0_859
	v_readlane_b32 s4, v252, 0
	s_mul_i32 s33, s4, s58
	s_add_u32 s4, s54, 0x22a2200
	s_addc_u32 s5, s55, 0
	s_add_u32 s8, s54, 0x22a2400
	s_addc_u32 s9, s55, 0
	s_add_u32 s10, s54, 0x22a2500
	s_addc_u32 s11, s55, 0
	s_add_u32 s14, s54, 0x22a2600
	s_addc_u32 s15, s55, 0
	s_add_u32 s16, s54, 0x22a2700
	s_addc_u32 s17, s55, 0
	s_add_u32 s18, s54, 0x22a2800
	s_addc_u32 s19, s55, 0
	s_add_u32 s20, s54, 0x22a2900
	s_addc_u32 s21, s55, 0
	s_add_u32 s22, s54, 0x22a2a00
	s_addc_u32 s23, s55, 0
	s_add_u32 s24, s54, 0x22a2b00
	s_addc_u32 s25, s55, 0
	s_add_u32 s26, s54, 0x22a2c00
	s_addc_u32 s27, s55, 0
	s_add_u32 s28, s54, 0x22a2d00
	s_addc_u32 s29, s55, 0
	s_add_u32 s30, s54, 0x22a2e00
	s_addc_u32 s31, s55, 0
	s_add_u32 s34, s54, 0x22a2f00
	s_addc_u32 s35, s55, 0
	s_add_u32 s40, s54, 0x22a3000
	s_addc_u32 s41, s55, 0
	s_add_u32 s42, s54, 0x22a3100
	s_addc_u32 s43, s55, 0
	s_add_u32 s44, s54, 0x22a3200
	s_addc_u32 s45, s55, 0
	s_add_u32 s46, s54, 0x22a3300
	s_mul_i32 s33, s33, s59
	s_addc_u32 s47, s55, 0
	s_mov_b32 s66, 1
	v_mov_b32_e32 v16, 0
	s_branch .LBB0_847

; __device__ __forceinline__ unsigned xb_ld(unsigned* p)              { return __hip_atomic_load(p, __ATOMIC_RELAXED, __HIP_MEMORY_SCOPE_AGENT); }
; __device__ __forceinline__ unsigned xb_add(unsigned* p, unsigned v) { return __hip_atomic_fetch_add(p, v, __ATOMIC_RELAXED, __HIP_MEMORY_SCOPE_AGENT); }
; #define XB_SPIN(cond, bar) do { unsigned _sp = 0; while (cond) { __builtin_amdgcn_s_sleep(1); \
;     if ((++_sp & 255u) == 0u) { if (xb_ld(&(bar)[XB_TMO])) break; if (_sp > XB_SPIN_CAP) { atomicAdd(&(bar)[XB_TMO], 1u); break; } } } } while (0)
; __device__ __forceinline__ void xcd_barrier(const XcdBarrier& b) {
;     ...
;             __builtin_amdgcn_fence(__ATOMIC_RELEASE, "agent");
;             asm volatile("s_waitcnt vmcnt(0)" ::: "memory");
;             const unsigned og = xb_add(&bar[XB_TOP], 1u);
;             const unsigned tg = og / nx;
;             if (og + 1u == (tg + 1u) * nx) xb_add(&bar[XB_TOPGEN], 1u);
;             else XB_SPIN(xb_ld(&bar[XB_TOPGEN]) == tg, bar);
;             __builtin_amdgcn_fence(__ATOMIC_ACQUIRE, "agent");
;             xb_add(&bar[XB_XGEN(b.x)], 1u);
;             asm volatile("s_waitcnt vmcnt(0)" ::: "memory");
.LBB0_892:
	s_or_b64 exec, exec, s[8:9]
	s_mov_b64 s[8:9], exec
	v_mbcnt_lo_u32_b32 v0, s8, 0
	v_mbcnt_hi_u32_b32 v0, s9, v0
	v_cmp_eq_u32_e32 vcc, 0, v0
	s_waitcnt vmcnt(0)
	s_and_saveexec_b64 s[10:11], vcc
	s_cbranch_execz .LBB0_894
	s_bcnt1_i32_b64 s3, s[8:9]
	v_mov_b32_e32 v0, 0x2000
	v_mov_b32_e32 v1, s3
	global_atomic_add v0, v1, s[4:5] offset:1024

; __device__ __forceinline__ unsigned xb_ld(unsigned* p)              { return __hip_atomic_load(p, __ATOMIC_RELAXED, __HIP_MEMORY_SCOPE_AGENT); }
; __device__ __forceinline__ void xcd_barrier_complete(unsigned* bar, unsigned x, unsigned& nloc, unsigned& nx) {
;     const unsigned G = gridDim.x * gridDim.y * gridDim.z;
;     unsigned sum, cnt, mine, sp = 0u;
;     for (;;) {
;         sum = 0u; cnt = 0u; mine = 0u;
; #pragma unroll
;         for (unsigned j = 0; j < 16; ++j) { const unsigned c = xb_ld(&bar[XB_XCNT(j)]); sum += c; cnt += (c > 0u) ? 1u : 0u; mine = (j == x) ? c : mine; }
; __device__ __forceinline__ void xcd_barrier(const XcdBarrier& b) {
;     asm volatile("s_waitcnt vmcnt(0)" ::: "memory");
;     __syncthreads();
;     if (threadIdx.x == 0) {
;         unsigned* bar = b.bar;
;         __builtin_amdgcn_s_waitcnt(0);
;         unsigned nloc = b.st[0], nx = b.st[1];
;         if (nloc == 0u) { xcd_barrier_complete(bar, b.x, nloc, nx); b.st[0] = nloc; b.st[1] = nx; }
.LBB0_934:
	s_cmp_lt_i32 s56, 9
	s_cselect_b64 s[4:5], -1, 0
	s_cmp_gt_i32 s57, 8
	s_cselect_b64 s[0:1], -1, 0
	s_and_b64 s[0:1], s[4:5], s[0:1]
	s_andn2_b64 vcc, exec, s[0:1]
	s_cbranch_vccnz .LBB0_1079
	s_andn2_b64 vcc, exec, s[6:7]
	s_cbranch_vccnz .LBB0_989
	s_getreg_b32 s3, hwreg(HW_REG_XCC_ID, 0, 4)
	s_waitcnt vmcnt(0)
	v_cmp_eq_u32_e32 vcc, 0, v178
	s_waitcnt vmcnt(0) lgkmcnt(0)
	s_barrier
	s_and_saveexec_b64 s[0:1], vcc
	s_cbranch_execz .LBB0_988
	buffer_inv sc1
	s_add_i32 s6, 0, 0x23ff0
	v_mov_b32_e32 v0, s6
	s_waitcnt vmcnt(0) expcnt(0) lgkmcnt(0)
	ds_read_b32 v2, v0
	s_add_i32 s6, 0, 0x23ff4
	v_mov_b32_e32 v0, s6
	ds_read_b32 v0, v0
	s_and_b32 s3, s3, 15
	s_waitcnt lgkmcnt(1)
	v_cmp_ne_u32_e32 vcc, 0, v2
	s_cbranch_vccnz .LBB0_952
	v_readlane_b32 s6, v252, 0
	s_mul_i32 s33, s6, s58
	s_add_u32 s6, s54, 0x22a2200
	s_addc_u32 s7, s55, 0
	s_add_u32 s8, s54, 0x22a2400
	s_addc_u32 s9, s55, 0
	s_add_u32 s10, s54, 0x22a2500
	s_addc_u32 s11, s55, 0
	s_add_u32 s14, s54, 0x22a2600
	s_addc_u32 s15, s55, 0
	s_add_u32 s16, s54, 0x22a2700
	s_addc_u32 s17, s55, 0
	s_add_u32 s18, s54, 0x22a2800
	s_addc_u32 s19, s55, 0
	s_add_u32 s20, s54, 0x22a2900
	s_addc_u32 s21, s55, 0
	s_add_u32 s22, s54, 0x22a2a00
	s_addc_u32 s23, s55, 0
	s_add_u32 s24, s54, 0x22a2b00
	s_addc_u32 s25, s55, 0
	s_add_u32 s26, s54, 0x22a2c00
	s_addc_u32 s27, s55, 0
	s_add_u32 s28, s54, 0x22a2d00
	s_addc_u32 s29, s55, 0
	s_add_u32 s30, s54, 0x22a2e00
	s_addc_u32 s31, s55, 0
	s_add_u32 s34, s54, 0x22a2f00
	s_addc_u32 s35, s55, 0
	s_add_u32 s40, s54, 0x22a3000
	s_addc_u32 s41, s55, 0
	s_add_u32 s42, s54, 0x22a3100
	s_addc_u32 s43, s55, 0
	s_add_u32 s44, s54, 0x22a3200
	s_addc_u32 s45, s55, 0
	s_add_u32 s46, s54, 0x22a3300
	s_mul_i32 s33, s33, s59
	s_addc_u32 s47, s55, 0
	s_mov_b32 s66, 1
	v_mov_b32_e32 v16, 0
	s_branch .LBB0_940

; __device__ __forceinline__ unsigned xb_ld(unsigned* p)              { return __hip_atomic_load(p, __ATOMIC_RELAXED, __HIP_MEMORY_SCOPE_AGENT); }
; __device__ __forceinline__ void xcd_barrier_complete(unsigned* bar, unsigned x, unsigned& nloc, unsigned& nx) {
;     const unsigned G = gridDim.x * gridDim.y * gridDim.z;
;     unsigned sum, cnt, mine, sp = 0u;
;     for (;;) {
;         sum = 0u; cnt = 0u; mine = 0u;
; #pragma unroll
;         for (unsigned j = 0; j < 16; ++j) { const unsigned c = xb_ld(&bar[XB_XCNT(j)]); sum += c; cnt += (c > 0u) ? 1u : 0u; mine = (j == x) ? c : mine; }
; __device__ __forceinline__ void xcd_barrier(const XcdBarrier& b) {
;     asm volatile("s_waitcnt vmcnt(0)" ::: "memory");
;     __syncthreads();
;     if (threadIdx.x == 0) {
;         unsigned* bar = b.bar;
;         __builtin_amdgcn_s_waitcnt(0);
;         unsigned nloc = b.st[0], nx = b.st[1];
;         if (nloc == 0u) { xcd_barrier_complete(bar, b.x, nloc, nx); b.st[0] = nloc; b.st[1] = nx; }
.LBB0_1079:
	s_cmp_lt_i32 s56, 10
	s_cselect_b64 s[6:7], -1, 0
	s_cmp_gt_i32 s57, 9
	s_cselect_b64 s[0:1], -1, 0
	s_and_b64 s[0:1], s[6:7], s[0:1]
	s_andn2_b64 vcc, exec, s[0:1]
	s_cbranch_vccnz .LBB0_1139
	s_andn2_b64 vcc, exec, s[4:5]
	s_cbranch_vccnz .LBB0_1134
	s_getreg_b32 s3, hwreg(HW_REG_XCC_ID, 0, 4)
	s_waitcnt vmcnt(0)
	v_cmp_eq_u32_e32 vcc, 0, v178
	s_waitcnt vmcnt(0) lgkmcnt(0)
	s_barrier
	s_and_saveexec_b64 s[0:1], vcc
	s_cbranch_execz .LBB0_1133
	buffer_inv sc1
	s_add_i32 s4, 0, 0x23ff0
	v_mov_b32_e32 v0, s4
	s_waitcnt vmcnt(0) expcnt(0) lgkmcnt(0)
	ds_read_b32 v2, v0
	s_add_i32 s4, 0, 0x23ff4
	v_mov_b32_e32 v0, s4
	ds_read_b32 v0, v0
	s_and_b32 s3, s3, 15
	s_waitcnt lgkmcnt(1)
	v_cmp_ne_u32_e32 vcc, 0, v2
	s_cbranch_vccnz .LBB0_1097
	v_readlane_b32 s4, v252, 0
	s_mul_i32 s33, s4, s58
	s_add_u32 s4, s54, 0x22a2200
	s_addc_u32 s5, s55, 0
	s_add_u32 s8, s54, 0x22a2400
	s_addc_u32 s9, s55, 0
	s_add_u32 s10, s54, 0x22a2500
	s_addc_u32 s11, s55, 0
	s_add_u32 s14, s54, 0x22a2600
	s_addc_u32 s15, s55, 0
	s_add_u32 s16, s54, 0x22a2700
	s_addc_u32 s17, s55, 0
	s_add_u32 s18, s54, 0x22a2800
	s_addc_u32 s19, s55, 0
	s_add_u32 s20, s54, 0x22a2900
	s_addc_u32 s21, s55, 0
	s_add_u32 s22, s54, 0x22a2a00
	s_addc_u32 s23, s55, 0
	s_add_u32 s24, s54, 0x22a2b00
	s_addc_u32 s25, s55, 0
	s_add_u32 s26, s54, 0x22a2c00
	s_addc_u32 s27, s55, 0
	s_add_u32 s28, s54, 0x22a2d00
	s_addc_u32 s29, s55, 0
	s_add_u32 s30, s54, 0x22a2e00
	s_addc_u32 s31, s55, 0
	s_add_u32 s34, s54, 0x22a2f00
	s_addc_u32 s35, s55, 0
	s_add_u32 s40, s54, 0x22a3000
	s_addc_u32 s41, s55, 0
	s_add_u32 s42, s54, 0x22a3100
	s_addc_u32 s43, s55, 0
	s_add_u32 s44, s54, 0x22a3200
	s_addc_u32 s45, s55, 0
	s_add_u32 s46, s54, 0x22a3300
	s_mul_i32 s33, s33, s59
	s_addc_u32 s47, s55, 0
	s_mov_b32 s66, 1
	v_mov_b32_e32 v16, 0
	s_branch .LBB0_1085

; __device__ __forceinline__ unsigned xb_ld(unsigned* p)              { return __hip_atomic_load(p, __ATOMIC_RELAXED, __HIP_MEMORY_SCOPE_AGENT); }
; __device__ __forceinline__ void xcd_barrier_complete(unsigned* bar, unsigned x, unsigned& nloc, unsigned& nx) {
;     const unsigned G = gridDim.x * gridDim.y * gridDim.z;
;     unsigned sum, cnt, mine, sp = 0u;
;     for (;;) {
;         sum = 0u; cnt = 0u; mine = 0u;
; #pragma unroll
;         for (unsigned j = 0; j < 16; ++j) { const unsigned c = xb_ld(&bar[XB_XCNT(j)]); sum += c; cnt += (c > 0u) ? 1u : 0u; mine = (j == x) ? c : mine; }
; __device__ __forceinline__ void xcd_barrier(const XcdBarrier& b) {
;     asm volatile("s_waitcnt vmcnt(0)" ::: "memory");
;     __syncthreads();
;     if (threadIdx.x == 0) {
;         unsigned* bar = b.bar;
;         __builtin_amdgcn_s_waitcnt(0);
;         unsigned nloc = b.st[0], nx = b.st[1];
;         if (nloc == 0u) { xcd_barrier_complete(bar, b.x, nloc, nx); b.st[0] = nloc; b.st[1] = nx; }
.LBB0_1139:
	s_cmp_lt_i32 s56, 11
	s_cselect_b64 s[4:5], -1, 0
	s_cmp_gt_i32 s57, 10
	s_cselect_b64 s[0:1], -1, 0
	s_and_b64 s[0:1], s[4:5], s[0:1]
	s_andn2_b64 vcc, exec, s[0:1]
	s_cbranch_vccnz .LBB0_1210
	s_andn2_b64 vcc, exec, s[6:7]
	s_cbranch_vccnz .LBB0_1194
	s_getreg_b32 s3, hwreg(HW_REG_XCC_ID, 0, 4)
	s_waitcnt vmcnt(0)
	v_cmp_eq_u32_e32 vcc, 0, v178
	s_waitcnt vmcnt(0) lgkmcnt(0)
	s_barrier
	s_and_saveexec_b64 s[0:1], vcc
	s_cbranch_execz .LBB0_1193
	buffer_inv sc1
	s_add_i32 s6, 0, 0x23ff0
	v_mov_b32_e32 v0, s6
	s_waitcnt vmcnt(0) expcnt(0) lgkmcnt(0)
	ds_read_b32 v2, v0
	s_add_i32 s6, 0, 0x23ff4
	v_mov_b32_e32 v0, s6
	ds_read_b32 v0, v0
	s_and_b32 s3, s3, 15
	s_waitcnt lgkmcnt(1)
	v_cmp_ne_u32_e32 vcc, 0, v2
	s_cbranch_vccnz .LBB0_1157
	v_readlane_b32 s6, v252, 0
	s_mul_i32 s33, s6, s58
	s_add_u32 s6, s54, 0x22a2200
	s_addc_u32 s7, s55, 0
	s_add_u32 s8, s54, 0x22a2400
	s_addc_u32 s9, s55, 0
	s_add_u32 s10, s54, 0x22a2500
	s_addc_u32 s11, s55, 0
	s_add_u32 s14, s54, 0x22a2600
	s_addc_u32 s15, s55, 0
	s_add_u32 s16, s54, 0x22a2700
	s_addc_u32 s17, s55, 0
	s_add_u32 s18, s54, 0x22a2800
	s_addc_u32 s19, s55, 0
	s_add_u32 s20, s54, 0x22a2900
	s_addc_u32 s21, s55, 0
	s_add_u32 s22, s54, 0x22a2a00
	s_addc_u32 s23, s55, 0
	s_add_u32 s24, s54, 0x22a2b00
	s_addc_u32 s25, s55, 0
	s_add_u32 s26, s54, 0x22a2c00
	s_addc_u32 s27, s55, 0
	s_add_u32 s28, s54, 0x22a2d00
	s_addc_u32 s29, s55, 0
	s_add_u32 s30, s54, 0x22a2e00
	s_addc_u32 s31, s55, 0
	s_add_u32 s34, s54, 0x22a2f00
	s_addc_u32 s35, s55, 0
	s_add_u32 s36, s54, 0x22a3000
	s_addc_u32 s37, s55, 0
	s_add_u32 s38, s54, 0x22a3100
	s_addc_u32 s39, s55, 0
	s_add_u32 s40, s54, 0x22a3200
	s_addc_u32 s41, s55, 0
	s_add_u32 s42, s54, 0x22a3300
	s_mul_i32 s33, s33, s59
	s_addc_u32 s43, s55, 0
	s_mov_b32 s50, 1
	v_mov_b32_e32 v16, 0
	s_branch .LBB0_1145

; __device__ __forceinline__ unsigned xb_ld(unsigned* p)              { return __hip_atomic_load(p, __ATOMIC_RELAXED, __HIP_MEMORY_SCOPE_AGENT); }
; __device__ __forceinline__ void xcd_barrier_complete(unsigned* bar, unsigned x, unsigned& nloc, unsigned& nx) {
;     const unsigned G = gridDim.x * gridDim.y * gridDim.z;
;     unsigned sum, cnt, mine, sp = 0u;
;     for (;;) {
;         sum = 0u; cnt = 0u; mine = 0u;
; #pragma unroll
;         for (unsigned j = 0; j < 16; ++j) { const unsigned c = xb_ld(&bar[XB_XCNT(j)]); sum += c; cnt += (c > 0u) ? 1u : 0u; mine = (j == x) ? c : mine; }
; __device__ __forceinline__ void xcd_barrier(const XcdBarrier& b) {
;     asm volatile("s_waitcnt vmcnt(0)" ::: "memory");
;     __syncthreads();
;     if (threadIdx.x == 0) {
;         unsigned* bar = b.bar;
;         __builtin_amdgcn_s_waitcnt(0);
;         unsigned nloc = b.st[0], nx = b.st[1];
;         if (nloc == 0u) { xcd_barrier_complete(bar, b.x, nloc, nx); b.st[0] = nloc; b.st[1] = nx; }
.LBB0_1210:
	s_cmp_lt_i32 s56, 12
	s_cselect_b64 s[10:11], -1, 0
	s_cmp_gt_i32 s57, 11
	s_cselect_b64 s[0:1], -1, 0
	s_and_b64 s[0:1], s[10:11], s[0:1]
	s_andn2_b64 vcc, exec, s[0:1]
	s_cbranch_vccnz .LBB0_1307
	s_andn2_b64 vcc, exec, s[4:5]
	s_cbranch_vccnz .LBB0_1265
	s_getreg_b32 s3, hwreg(HW_REG_XCC_ID, 0, 4)
	s_waitcnt vmcnt(0)
	v_cmp_eq_u32_e32 vcc, 0, v178
	s_waitcnt vmcnt(0) lgkmcnt(0)
	s_barrier
	s_and_saveexec_b64 s[0:1], vcc
	s_cbranch_execz .LBB0_1264
	buffer_inv sc1
	s_add_i32 s4, 0, 0x23ff0
	v_mov_b32_e32 v0, s4
	s_waitcnt vmcnt(0) expcnt(0) lgkmcnt(0)
	ds_read_b32 v2, v0
	s_add_i32 s4, 0, 0x23ff4
	v_mov_b32_e32 v0, s4
	ds_read_b32 v0, v0
	s_and_b32 s3, s3, 15
	s_waitcnt lgkmcnt(1)
	v_cmp_ne_u32_e32 vcc, 0, v2
	s_cbranch_vccnz .LBB0_1228
	v_readlane_b32 s4, v252, 0
	s_mul_i32 s33, s4, s58
	s_add_u32 s4, s54, 0x22a2200
	s_addc_u32 s5, s55, 0
	s_add_u32 s6, s54, 0x22a2400
	s_addc_u32 s7, s55, 0
	s_add_u32 s8, s54, 0x22a2500
	s_addc_u32 s9, s55, 0
	s_add_u32 s14, s54, 0x22a2600
	s_addc_u32 s15, s55, 0
	s_add_u32 s16, s54, 0x22a2700
	s_addc_u32 s17, s55, 0
	s_add_u32 s18, s54, 0x22a2800
	s_addc_u32 s19, s55, 0
	s_add_u32 s20, s54, 0x22a2900
	s_addc_u32 s21, s55, 0
	s_add_u32 s22, s54, 0x22a2a00
	s_addc_u32 s23, s55, 0
	s_add_u32 s24, s54, 0x22a2b00
	s_addc_u32 s25, s55, 0
	s_add_u32 s26, s54, 0x22a2c00
	s_addc_u32 s27, s55, 0
	s_add_u32 s28, s54, 0x22a2d00
	s_addc_u32 s29, s55, 0
	s_add_u32 s30, s54, 0x22a2e00
	s_addc_u32 s31, s55, 0
	s_add_u32 s34, s54, 0x22a2f00
	s_addc_u32 s35, s55, 0
	s_add_u32 s36, s54, 0x22a3000
	s_addc_u32 s37, s55, 0
	s_add_u32 s38, s54, 0x22a3100
	s_addc_u32 s39, s55, 0
	s_add_u32 s40, s54, 0x22a3200
	s_addc_u32 s41, s55, 0
	s_add_u32 s42, s54, 0x22a3300
	s_mul_i32 s33, s33, s59
	s_addc_u32 s43, s55, 0
	s_mov_b32 s50, 1
	v_mov_b32_e32 v16, 0
	s_branch .LBB0_1216

; __device__ __forceinline__ unsigned xb_ld(unsigned* p)              { return __hip_atomic_load(p, __ATOMIC_RELAXED, __HIP_MEMORY_SCOPE_AGENT); }
; __device__ __forceinline__ void xcd_barrier_complete(unsigned* bar, unsigned x, unsigned& nloc, unsigned& nx) {
;     const unsigned G = gridDim.x * gridDim.y * gridDim.z;
;     unsigned sum, cnt, mine, sp = 0u;
;     for (;;) {
;         sum = 0u; cnt = 0u; mine = 0u;
; #pragma unroll
;         for (unsigned j = 0; j < 16; ++j) { const unsigned c = xb_ld(&bar[XB_XCNT(j)]); sum += c; cnt += (c > 0u) ? 1u : 0u; mine = (j == x) ? c : mine; }
; __device__ __forceinline__ void xcd_barrier(const XcdBarrier& b) {
;     asm volatile("s_waitcnt vmcnt(0)" ::: "memory");
;     __syncthreads();
;     if (threadIdx.x == 0) {
;         unsigned* bar = b.bar;
;         __builtin_amdgcn_s_waitcnt(0);
;         unsigned nloc = b.st[0], nx = b.st[1];
;         if (nloc == 0u) { xcd_barrier_complete(bar, b.x, nloc, nx); b.st[0] = nloc; b.st[1] = nx; }
.LBB0_1307:
	s_cmp_lt_i32 s56, 13
	s_cselect_b64 s[6:7], -1, 0
	s_cmp_gt_i32 s57, 12
	s_cselect_b64 s[0:1], -1, 0
	s_and_b64 s[0:1], s[6:7], s[0:1]
	s_andn2_b64 vcc, exec, s[0:1]
	s_cbranch_vccnz .LBB0_1460
	s_andn2_b64 vcc, exec, s[10:11]
	s_cbranch_vccnz .LBB0_1362
	s_getreg_b32 s3, hwreg(HW_REG_XCC_ID, 0, 4)
	s_waitcnt vmcnt(0)
	v_cmp_eq_u32_e32 vcc, 0, v178
	s_waitcnt vmcnt(0) lgkmcnt(0)
	s_barrier
	s_and_saveexec_b64 s[0:1], vcc
	s_cbranch_execz .LBB0_1361
	buffer_inv sc1
	s_add_i32 s4, 0, 0x23ff0
	v_mov_b32_e32 v0, s4
	s_waitcnt vmcnt(0) expcnt(0) lgkmcnt(0)
	ds_read_b32 v2, v0
	s_add_i32 s4, 0, 0x23ff4
	v_mov_b32_e32 v0, s4
	ds_read_b32 v0, v0
	s_and_b32 s3, s3, 15
	s_waitcnt lgkmcnt(1)
	v_cmp_ne_u32_e32 vcc, 0, v2
	s_cbranch_vccnz .LBB0_1325
	v_readlane_b32 s4, v252, 0
	s_mul_i32 s33, s4, s58
	s_add_u32 s4, s54, 0x22a2200
	s_addc_u32 s5, s55, 0
	s_add_u32 s8, s54, 0x22a2400
	s_addc_u32 s9, s55, 0
	s_add_u32 s10, s54, 0x22a2500
	s_addc_u32 s11, s55, 0
	s_add_u32 s14, s54, 0x22a2600
	s_addc_u32 s15, s55, 0
	s_add_u32 s16, s54, 0x22a2700
	s_addc_u32 s17, s55, 0
	s_add_u32 s18, s54, 0x22a2800
	s_addc_u32 s19, s55, 0
	s_add_u32 s20, s54, 0x22a2900
	s_addc_u32 s21, s55, 0
	s_add_u32 s22, s54, 0x22a2a00
	s_addc_u32 s23, s55, 0
	s_add_u32 s24, s54, 0x22a2b00
	s_addc_u32 s25, s55, 0
	s_add_u32 s26, s54, 0x22a2c00
	s_addc_u32 s27, s55, 0
	s_add_u32 s28, s54, 0x22a2d00
	s_addc_u32 s29, s55, 0
	s_add_u32 s30, s54, 0x22a2e00
	s_addc_u32 s31, s55, 0
	s_add_u32 s34, s54, 0x22a2f00
	s_addc_u32 s35, s55, 0
	s_add_u32 s36, s54, 0x22a3000
	s_addc_u32 s37, s55, 0
	s_add_u32 s38, s54, 0x22a3100
	s_addc_u32 s39, s55, 0
	s_add_u32 s40, s54, 0x22a3200
	s_addc_u32 s41, s55, 0
	s_add_u32 s42, s54, 0x22a3300
	s_mul_i32 s33, s33, s59
	s_addc_u32 s43, s55, 0
	s_mov_b32 s50, 1
	v_mov_b32_e32 v16, 0
	s_branch .LBB0_1313

; __device__ __forceinline__ unsigned xb_ld(unsigned* p)              { return __hip_atomic_load(p, __ATOMIC_RELAXED, __HIP_MEMORY_SCOPE_AGENT); }
; __device__ __forceinline__ void xcd_barrier_complete(unsigned* bar, unsigned x, unsigned& nloc, unsigned& nx) {
;     const unsigned G = gridDim.x * gridDim.y * gridDim.z;
;     unsigned sum, cnt, mine, sp = 0u;
;     for (;;) {
;         sum = 0u; cnt = 0u; mine = 0u;
; #pragma unroll
;         for (unsigned j = 0; j < 16; ++j) { const unsigned c = xb_ld(&bar[XB_XCNT(j)]); sum += c; cnt += (c > 0u) ? 1u : 0u; mine = (j == x) ? c : mine; }
; __device__ __forceinline__ void xcd_barrier(const XcdBarrier& b) {
;     asm volatile("s_waitcnt vmcnt(0)" ::: "memory");
;     __syncthreads();
;     if (threadIdx.x == 0) {
;         unsigned* bar = b.bar;
;         __builtin_amdgcn_s_waitcnt(0);
;         unsigned nloc = b.st[0], nx = b.st[1];
;         if (nloc == 0u) { xcd_barrier_complete(bar, b.x, nloc, nx); b.st[0] = nloc; b.st[1] = nx; }
.LBB0_1460:
	s_cmp_lt_i32 s56, 14
	s_cselect_b64 s[0:1], -1, 0
	s_cmp_gt_i32 s57, 13
	s_cselect_b64 s[4:5], -1, 0
	s_and_b64 s[0:1], s[0:1], s[4:5]
	s_andn2_b64 vcc, exec, s[0:1]
	s_cbranch_vccnz .LBB0_1520
	s_andn2_b64 vcc, exec, s[6:7]
	s_cbranch_vccnz .LBB0_1515
	s_getreg_b32 s3, hwreg(HW_REG_XCC_ID, 0, 4)
	s_waitcnt vmcnt(0)
	v_cmp_eq_u32_e32 vcc, 0, v178
	s_waitcnt vmcnt(0) lgkmcnt(0)
	s_barrier
	s_and_saveexec_b64 s[0:1], vcc
	s_cbranch_execz .LBB0_1514
	buffer_inv sc1
	s_add_i32 s4, 0, 0x23ff0
	v_mov_b32_e32 v0, s4
	s_waitcnt vmcnt(0) expcnt(0) lgkmcnt(0)
	ds_read_b32 v2, v0
	s_add_i32 s4, 0, 0x23ff4
	v_mov_b32_e32 v0, s4
	ds_read_b32 v0, v0
	s_and_b32 s3, s3, 15
	s_waitcnt lgkmcnt(1)
	v_cmp_ne_u32_e32 vcc, 0, v2
	s_cbranch_vccnz .LBB0_1478
	v_readlane_b32 s4, v252, 0
	s_mul_i32 s33, s4, s58
	s_add_u32 s4, s54, 0x22a2200
	s_addc_u32 s5, s55, 0
	s_add_u32 s6, s54, 0x22a2400
	s_addc_u32 s7, s55, 0
	s_add_u32 s8, s54, 0x22a2500
	s_addc_u32 s9, s55, 0
	s_add_u32 s10, s54, 0x22a2600
	s_addc_u32 s11, s55, 0
	s_add_u32 s14, s54, 0x22a2700
	s_addc_u32 s15, s55, 0
	s_add_u32 s16, s54, 0x22a2800
	s_addc_u32 s17, s55, 0
	s_add_u32 s18, s54, 0x22a2900
	s_addc_u32 s19, s55, 0
	s_add_u32 s20, s54, 0x22a2a00
	s_addc_u32 s21, s55, 0
	s_add_u32 s22, s54, 0x22a2b00
	s_addc_u32 s23, s55, 0
	s_add_u32 s24, s54, 0x22a2c00
	s_addc_u32 s25, s55, 0
	s_add_u32 s26, s54, 0x22a2d00
	s_addc_u32 s27, s55, 0
	s_add_u32 s28, s54, 0x22a2e00
	s_addc_u32 s29, s55, 0
	s_add_u32 s30, s54, 0x22a2f00
	s_addc_u32 s31, s55, 0
	s_add_u32 s34, s54, 0x22a3000
	s_addc_u32 s35, s55, 0
	s_add_u32 s36, s54, 0x22a3100
	s_addc_u32 s37, s55, 0
	s_add_u32 s38, s54, 0x22a3200
	s_addc_u32 s39, s55, 0
	s_add_u32 s40, s54, 0x22a3300
	s_mul_i32 s33, s33, s59
	s_addc_u32 s41, s55, 0
	s_mov_b32 s48, 1
	v_mov_b32_e32 v16, 0
	s_branch .LBB0_1466
